# filler transposes (w_glu/w_out, done by idle workgroups in the last in-projection round) store write-through
# baseline (speedup 1.0000x reference)
.LBB0_296:
	v_mad_i64_i32 v[76:77], s[6:7], s8, v33, 0
	s_lshl_b32 s6, s3, 6
	s_add_i32 s67, s67, s63
	v_lshl_add_u64 v[76:77], v[76:77], 1, s[10:11]
	s_ashr_i32 s7, s6, 31
	s_add_i32 s3, s65, s67
	v_lshl_add_u64 v[76:77], s[6:7], 1, v[76:77]
	v_mov_b32_e32 v33, v129
	s_addk_i32 s3, 0x500
	v_lshl_add_u64 v[80:81], v[76:77], 0, v[32:33]
	s_cmpk_lt_i32 s3, 0x800
	s_waitcnt lgkmcnt(14)
	v_cvt_pk_bf16_f32 v76, v53, v60
	v_cvt_pk_bf16_f32 v77, v61, v67
	v_cvt_pk_bf16_f32 v78, v68, v72
	v_cvt_pk_bf16_f32 v79, v73, v75
	global_store_dwordx4 v[80:81], v[76:79], off sc1
	v_cvt_pk_bf16_f32 v60, v47, v54
	v_cvt_pk_bf16_f32 v61, v55, v62
	v_cvt_pk_bf16_f32 v62, v63, v69
	v_cvt_pk_bf16_f32 v63, v70, v74
	global_store_dwordx4 v[80:81], v[60:63], off offset:16 sc1
	v_cvt_pk_bf16_f32 v54, v41, v49
	s_waitcnt lgkmcnt(12)
	v_cvt_pk_bf16_f32 v55, v50, v56
	s_waitcnt lgkmcnt(10)
	v_cvt_pk_bf16_f32 v56, v57, v64
	s_waitcnt lgkmcnt(8)
	v_cvt_pk_bf16_f32 v57, v65, v71
	global_store_dwordx4 v[80:81], v[54:57], off offset:32 sc1
	s_waitcnt lgkmcnt(6)
	v_cvt_pk_bf16_f32 v50, v39, v43
	s_waitcnt lgkmcnt(4)
	v_cvt_pk_bf16_f32 v51, v45, v51
	s_waitcnt lgkmcnt(2)
	v_cvt_pk_bf16_f32 v52, v52, v58
	s_waitcnt lgkmcnt(0)
	v_cvt_pk_bf16_f32 v53, v59, v66
	global_store_dwordx4 v[80:81], v[50:53], off offset:48 sc1
	s_barrier
	s_cbranch_scc0 .LBB0_338
